# v24 + EpiGlu0: issue the eight row-scale loads before the last MFMA block of the K-loop and drop the epilogue vmcnt ladder
# baseline (speedup 1.0000x reference)
;     __device__ __forceinline__ unsigned poll_issue(const Unit& u) const { return (dep && threadIdx.x < 64) ? __hip_atomic_load(dep + 16 * u.pm, __ATOMIC_RELAXED, __HIP_MEMORY_SCOPE_AGENT) : 0u; }
; #define PG8_STAGE(bufoff, gbase, voff) do { _Pragma("unroll") for (int _i = 0; _i < 2; ++_i) \
;         __builtin_amdgcn_global_load_lds((const unsigned*)((const char*)(gbase) + (voff)[_i]), (PG8_LAS unsigned*)(lds + (bufoff) + ldsw + _i * 8192), 16, 0, 0); } while (0)
; #define PG8_STAGEA(bufoff, gbase, voff) do { _Pragma("unroll") for (int _i = 0; _i < 2; ++_i) \
;         __builtin_amdgcn_global_load_lds((const unsigned*)((const char*)(gbase) + (voff)[_i]), (PG8_LAS unsigned*)(lds + (bufoff) + ldsw + _i * 8192), 16, 0, A_SC1 ? 16 : 0); } while (0)
; #define PG8_LDA(dst, b, h) do { _Pragma("unroll") for (int m = 0; m < 4; ++m) _Pragma("unroll") for (int k = 0; k < 2; ++k) dst[m][k] = *(const PG8_LAS bf16x8*)(lds + PG8_SA(b, h) + aoff + m * 2048 + k * 1024); } while (0)
; #define PG8_WAIT_V(n) asm volatile("s_waitcnt vmcnt(" #n ")" ::: "memory")
; #define PG8_WAIT_L(n) asm volatile("s_waitcnt lgkmcnt(" #n ")" ::: "memory")
; template <class Epi, class Sched, bool ALIGN_EPI = false, bool SP2 = false, bool A_SC1 = false>
; __device__ __forceinline__ void gemm_phase(PG8_LAS unsigned char* lds, const Gemm g, const Sched& S, const Epi& E, const int tid) {
;     ...
;             const char* a1 = cA + (size_t)(t + 1) * kstep;
;             const char* a2 = last ? nA : cA + (size_t)(t + 2) * kstep; const char* b2 = last ? nB : cB + (size_t)(t + 2) * kstep;
;             const char* a3 = a2 + kstep; const char* b3 = b2 + kstep;
;             if (has_next) { if (t == nt - 6) pollv = S.poll_issue(nxt); else if (t == nt - 4) S.poll_check(pollv); }
;             if (last && has_next) S.a_ready_next(nxt);
;             if constexpr (SP2) {
;             PG8_LDB(B0, 0, 0); PG8_LDB(B1, 0, 1); PG8_SCHED; PG8_LDA(At, 0, 0); PG8_STAGEA(PG8_SA(1, 1), a1 + hstep, voffA);
;             PG8_WAIT_V(8); PG8_WAIT_L(0); PG8_BAR; PG8_MMA(0, 0, At, B0); PG8_MMA(0, 1, At, B1); PG8_BAR; PG8_SCHED;
;             PG8_LDA(At, 0, 1); PG8_STAGE(PG8_SB(0, 0), b2, voffB); PG8_STAGE(PG8_SB(0, 1), b2 + hstep, voffB); PG8_STAGEA(PG8_SA(0, 0), a2, voffA);
;             PG8_WAIT_V(8); PG8_WAIT_L(0); PG8_BAR; PG8_MMA(1, 0, At, B0); PG8_MMA(1, 1, At, B1); PG8_BAR; PG8_SCHED;
.LBB0_780:
	s_lshl_b32 s36, s85, 7
	s_add_u32 s37, s8, s36
	s_addc_u32 s86, s9, 0
	s_add_u32 s80, s37, 0x100
	s_addc_u32 s81, s86, 0
	s_and_b64 s[78:79], s[38:39], exec
	s_cselect_b32 s81, s81, s55
	s_cselect_b32 s80, s80, s82
	s_add_u32 s36, s10, s36
	s_addc_u32 s78, s11, 0
	s_add_u32 s36, s36, 0x100
	s_addc_u32 s78, s78, 0
	s_and_b64 s[38:39], s[38:39], exec
	s_cselect_b32 s39, s78, s53
	s_cselect_b32 s38, s36, s83
	s_add_i32 s36, 0, 0x10000
	v_add_u32_e32 v139, s36, v146
	s_add_i32 s87, 0, 0x14000
	ds_read_b128 v[140:143], v139
	ds_read_b128 v[150:153], v139 offset:1024
	ds_read_b128 v[154:157], v139 offset:2048
	ds_read_b128 v[158:161], v139 offset:3072
	v_add_u32_e32 v139, s87, v146
	ds_read_b128 v[162:165], v139
	ds_read_b128 v[166:169], v139 offset:1024
	ds_read_b128 v[170:173], v139 offset:2048
	ds_read_b128 v[174:177], v139 offset:3072
	s_add_u32 s78, s37, 0x40080
	s_addc_u32 s79, s86, 0
	v_lshl_add_u64 v[144:145], s[78:79], 0, v[130:131]
	s_add_i32 m0, s5, 0xc000
	ds_read_b128 v[178:181], v148
	ds_read_b128 v[182:185], v148 offset:1024
	ds_read_b128 v[186:189], v148 offset:2048
	ds_read_b128 v[190:193], v148 offset:3072
	ds_read_b128 v[208:211], v148 offset:4096
	ds_read_b128 v[212:215], v148 offset:5120
	ds_read_b128 v[216:219], v148 offset:6144
	ds_read_b128 v[220:223], v148 offset:7168
	global_load_lds_dwordx4 v[144:145], off
	v_lshl_add_u64 v[144:145], s[78:79], 0, v[134:135]
	s_add_i32 m0, s5, 0xe000
	s_nop 0
	global_load_lds_dwordx4 v[144:145], off
	s_waitcnt vmcnt(8)
	s_waitcnt lgkmcnt(0)
	s_barrier
	s_setprio 1
	s_waitcnt lgkmcnt(0)
	v_mfma_f32_16x16x32_bf16 v[126:129], v[140:143], v[178:181], v[126:129]
	v_mfma_f32_16x16x32_bf16 v[122:125], v[154:157], v[178:181], v[122:125]
	v_mfma_f32_16x16x32_bf16 v[118:121], v[140:143], v[186:189], v[118:121]
	v_mfma_f32_16x16x32_bf16 v[114:117], v[154:157], v[186:189], v[114:117]
	v_mfma_f32_16x16x32_bf16 v[110:113], v[140:143], v[208:211], v[110:113]
	v_mfma_f32_16x16x32_bf16 v[106:109], v[154:157], v[208:211], v[106:109]
	v_mfma_f32_16x16x32_bf16 v[102:105], v[140:143], v[216:219], v[102:105]
	v_mfma_f32_16x16x32_bf16 v[98:101], v[154:157], v[216:219], v[98:101]
	v_mfma_f32_16x16x32_bf16 v[126:129], v[150:153], v[182:185], v[126:129]
	v_mfma_f32_16x16x32_bf16 v[122:125], v[158:161], v[182:185], v[122:125]
	v_mfma_f32_16x16x32_bf16 v[118:121], v[150:153], v[190:193], v[118:121]
	v_mfma_f32_16x16x32_bf16 v[114:117], v[158:161], v[190:193], v[114:117]
	v_mfma_f32_16x16x32_bf16 v[110:113], v[150:153], v[212:215], v[110:113]
	v_mfma_f32_16x16x32_bf16 v[106:109], v[158:161], v[212:215], v[106:109]
	v_mfma_f32_16x16x32_bf16 v[102:105], v[150:153], v[220:223], v[102:105]
	v_mfma_f32_16x16x32_bf16 v[98:101], v[158:161], v[220:223], v[98:101]
	s_setprio 0
	s_setprio 1
	v_mfma_f32_16x16x32_bf16 v[94:97], v[162:165], v[178:181], v[94:97]
	v_mfma_f32_16x16x32_bf16 v[90:93], v[170:173], v[178:181], v[90:93]
	v_mfma_f32_16x16x32_bf16 v[86:89], v[162:165], v[186:189], v[86:89]
	v_mfma_f32_16x16x32_bf16 v[82:85], v[170:173], v[186:189], v[82:85]
	v_mfma_f32_16x16x32_bf16 v[78:81], v[162:165], v[208:211], v[78:81]
	v_mfma_f32_16x16x32_bf16 v[74:77], v[170:173], v[208:211], v[74:77]
	v_mfma_f32_16x16x32_bf16 v[70:73], v[162:165], v[216:219], v[70:73]
	v_mfma_f32_16x16x32_bf16 v[66:69], v[170:173], v[216:219], v[66:69]
	v_mfma_f32_16x16x32_bf16 v[94:97], v[166:169], v[182:185], v[94:97]
	v_mfma_f32_16x16x32_bf16 v[90:93], v[174:177], v[182:185], v[90:93]
	v_mfma_f32_16x16x32_bf16 v[86:89], v[166:169], v[190:193], v[86:89]
	v_mfma_f32_16x16x32_bf16 v[82:85], v[174:177], v[190:193], v[82:85]
	v_mfma_f32_16x16x32_bf16 v[78:81], v[166:169], v[212:215], v[78:81]
	v_mfma_f32_16x16x32_bf16 v[74:77], v[174:177], v[212:215], v[74:77]
	v_mfma_f32_16x16x32_bf16 v[70:73], v[166:169], v[220:223], v[70:73]
	v_mfma_f32_16x16x32_bf16 v[66:69], v[174:177], v[220:223], v[66:69]
	s_setprio 0
	s_barrier
	s_add_i32 s36, s36, s3
	v_lshl_add_u64 v[144:145], s[38:39], 0, v[132:133]
	s_mov_b32 m0, s36
	ds_read_b128 v[178:181], v148 offset:16384
	ds_read_b128 v[182:185], v148 offset:17408
	ds_read_b128 v[186:189], v148 offset:18432
	ds_read_b128 v[190:193], v148 offset:19456
	ds_read_b128 v[208:211], v148 offset:20480
	ds_read_b128 v[212:215], v148 offset:21504
	ds_read_b128 v[216:219], v148 offset:22528
	ds_read_b128 v[220:223], v148 offset:23552
	global_load_lds_dwordx4 v[144:145], off
	s_add_i32 m0, s36, 0x2000
	s_add_u32 s78, s38, 0x40000
	v_lshl_add_u64 v[224:225], s[38:39], 0, v[136:137]
	s_addc_u32 s79, s39, 0
	s_add_i32 s36, s87, s3
	global_load_lds_dwordx4 v[224:225], off
	v_lshl_add_u64 v[226:227], s[78:79], 0, v[132:133]
	s_mov_b32 m0, s36
	v_lshl_add_u64 v[228:229], s[80:81], 0, v[134:135]
	global_load_lds_dwordx4 v[226:227], off
	v_lshl_add_u64 v[226:227], s[78:79], 0, v[136:137]
	s_add_i32 m0, s36, 0x2000
	s_nop 0
	global_load_lds_dwordx4 v[226:227], off
	v_lshl_add_u64 v[226:227], s[80:81], 0, v[130:131]
	s_mov_b32 m0, s5
	s_nop 0
	global_load_lds_dwordx4 v[226:227], off
	s_mov_b32 m0, s28
	s_nop 0
	global_load_lds_dwordx4 v[228:229], off
	s_waitcnt vmcnt(8)
	s_waitcnt lgkmcnt(0)
	s_barrier
; #define PG8_STAGEA(bufoff, gbase, voff) do { _Pragma("unroll") for (int _i = 0; _i < 2; ++_i) \
;         __builtin_amdgcn_global_load_lds((const unsigned*)((const char*)(gbase) + (voff)[_i]), (PG8_LAS unsigned*)(lds + (bufoff) + ldsw + _i * 8192), 16, 0, A_SC1 ? 16 : 0); } while (0)
; #define PG8_LDA(dst, b, h) do { _Pragma("unroll") for (int m = 0; m < 4; ++m) _Pragma("unroll") for (int k = 0; k < 2; ++k) dst[m][k] = *(const PG8_LAS bf16x8*)(lds + PG8_SA(b, h) + aoff + m * 2048 + k * 1024); } while (0)
; #define PG8_LDB(dst, b, h) do { _Pragma("unroll") for (int n = 0; n < 2; ++n) _Pragma("unroll") for (int k = 0; k < 2; ++k) dst[n][k] = *(const PG8_LAS bf16x8*)(lds + PG8_SB(b, h) + boff + n * 2048 + k * 1024); } while (0)
; #define PG8_MMA(ai, bj, At, Bt) do { __builtin_amdgcn_s_setprio(1); _Pragma("unroll") for (int m = 0; m < 4; ++m) _Pragma("unroll") for (int n = 0; n < 2; ++n) _Pragma("unroll") for (int k = 0; k < 2; ++k) \
;         acc[ai][bj][m][n] = __builtin_amdgcn_mfma_f32_16x16x32_bf16(Bt[n][k], At[m][k], acc[ai][bj][m][n], 0, 0, 0); __builtin_amdgcn_s_setprio(0); } while (0)
; #define PG8_WAIT_V(n) asm volatile("s_waitcnt vmcnt(" #n ")" ::: "memory")
; #define PG8_WAIT_L(n) asm volatile("s_waitcnt lgkmcnt(" #n ")" ::: "memory")
; #define PG8_BAR __builtin_amdgcn_s_barrier()
; #define PG8_SCHED __builtin_amdgcn_sched_barrier(0)
; template <class Epi, class Sched, bool ALIGN_EPI = false, bool SP2 = false, bool A_SC1 = false>
; __device__ __forceinline__ void gemm_phase(PG8_LAS unsigned char* lds, const Gemm g, const Sched& S, const Epi& E, const int tid) {
;     ...
;             PG8_WAIT_V(8); PG8_WAIT_L(0); PG8_BAR; PG8_MMA(1, 0, At, B0); PG8_MMA(1, 1, At, B1); PG8_BAR; PG8_SCHED;
;             PG8_LDB(B0, 1, 0); PG8_LDB(B1, 1, 1); PG8_SCHED; PG8_LDA(At, 1, 0); PG8_STAGEA(PG8_SA(0, 1), a2 + hstep, voffA);
;             PG8_WAIT_V(8); PG8_WAIT_L(0); PG8_BAR; PG8_MMA(0, 0, At, B0); PG8_MMA(0, 1, At, B1); PG8_BAR; PG8_SCHED;
	s_setprio 1
	s_waitcnt lgkmcnt(0)
	v_mfma_f32_16x16x32_bf16 v[62:65], v[140:143], v[178:181], v[62:65]
	v_mfma_f32_16x16x32_bf16 v[58:61], v[154:157], v[178:181], v[58:61]
	v_mfma_f32_16x16x32_bf16 v[54:57], v[140:143], v[186:189], v[54:57]
	v_mfma_f32_16x16x32_bf16 v[50:53], v[154:157], v[186:189], v[50:53]
	v_mfma_f32_16x16x32_bf16 v[46:49], v[140:143], v[208:211], v[46:49]
	v_mfma_f32_16x16x32_bf16 v[42:45], v[154:157], v[208:211], v[42:45]
	v_mfma_f32_16x16x32_bf16 v[38:41], v[140:143], v[216:219], v[38:41]
	v_mfma_f32_16x16x32_bf16 v[34:37], v[154:157], v[216:219], v[34:37]
	v_mfma_f32_16x16x32_bf16 v[62:65], v[150:153], v[182:185], v[62:65]
	v_mfma_f32_16x16x32_bf16 v[58:61], v[158:161], v[182:185], v[58:61]
	v_mfma_f32_16x16x32_bf16 v[54:57], v[150:153], v[190:193], v[54:57]
	v_mfma_f32_16x16x32_bf16 v[50:53], v[158:161], v[190:193], v[50:53]
	v_mfma_f32_16x16x32_bf16 v[46:49], v[150:153], v[212:215], v[46:49]
	v_mfma_f32_16x16x32_bf16 v[42:45], v[158:161], v[212:215], v[42:45]
	v_mfma_f32_16x16x32_bf16 v[38:41], v[150:153], v[220:223], v[38:41]
	v_mfma_f32_16x16x32_bf16 v[34:37], v[158:161], v[220:223], v[34:37]
	s_setprio 0
	s_setprio 1
	v_mfma_f32_16x16x32_bf16 v[30:33], v[162:165], v[178:181], v[30:33]
	v_mfma_f32_16x16x32_bf16 v[26:29], v[170:173], v[178:181], v[26:29]
	v_mfma_f32_16x16x32_bf16 v[22:25], v[162:165], v[186:189], v[22:25]
	v_mfma_f32_16x16x32_bf16 v[18:21], v[170:173], v[186:189], v[18:21]
	v_mfma_f32_16x16x32_bf16 v[14:17], v[162:165], v[208:211], v[14:17]
	v_mfma_f32_16x16x32_bf16 v[10:13], v[170:173], v[208:211], v[10:13]
	v_mfma_f32_16x16x32_bf16 v[6:9], v[162:165], v[216:219], v[6:9]
	v_mfma_f32_16x16x32_bf16 v[2:5], v[170:173], v[216:219], v[2:5]
	v_mfma_f32_16x16x32_bf16 v[30:33], v[166:169], v[182:185], v[30:33]
	v_mfma_f32_16x16x32_bf16 v[26:29], v[174:177], v[182:185], v[26:29]
	v_mfma_f32_16x16x32_bf16 v[22:25], v[166:169], v[190:193], v[22:25]
	v_mfma_f32_16x16x32_bf16 v[18:21], v[174:177], v[190:193], v[18:21]
	v_mfma_f32_16x16x32_bf16 v[14:17], v[166:169], v[212:215], v[14:17]
	v_mfma_f32_16x16x32_bf16 v[10:13], v[174:177], v[212:215], v[10:13]
	v_mfma_f32_16x16x32_bf16 v[6:9], v[166:169], v[220:223], v[6:9]
	v_mfma_f32_16x16x32_bf16 v[2:5], v[174:177], v[220:223], v[2:5]
	s_setprio 0
	s_barrier
	s_add_i32 s36, 0, 0x18000
	v_add_u32_e32 v139, s36, v146
	s_add_i32 s37, 0, 0x1c000
	ds_read_b128 v[140:143], v139
	ds_read_b128 v[150:153], v139 offset:1024
	ds_read_b128 v[154:157], v139 offset:2048
	ds_read_b128 v[158:161], v139 offset:3072
	v_add_u32_e32 v139, s37, v146
	ds_read_b128 v[162:165], v139
	ds_read_b128 v[166:169], v139 offset:1024
	ds_read_b128 v[170:173], v139 offset:2048
	ds_read_b128 v[174:177], v139 offset:3072
	s_add_u32 s78, s80, 0x40000
	s_addc_u32 s79, s81, 0
	s_mov_b32 m0, s29
	v_lshl_add_u64 v[242:243], s[78:79], 0, v[130:131]
	ds_read_b128 v[178:181], v148 offset:32768
	ds_read_b128 v[182:185], v148 offset:33792
	ds_read_b128 v[186:189], v148 offset:34816
	ds_read_b128 v[190:193], v148 offset:35840
	ds_read_b128 v[208:211], v148 offset:36864
	ds_read_b128 v[212:215], v148 offset:37888
	ds_read_b128 v[216:219], v148 offset:38912
	ds_read_b128 v[220:223], v148 offset:39936
	global_load_lds_dwordx4 v[242:243], off
	v_lshl_add_u64 v[242:243], s[78:79], 0, v[134:135]
	s_mov_b32 m0, s64
	s_nop 0
	global_load_lds_dwordx4 v[242:243], off
	s_waitcnt vmcnt(8)
	s_waitcnt lgkmcnt(0)
	s_barrier
	s_setprio 1
	s_waitcnt lgkmcnt(0)
	v_mfma_f32_16x16x32_bf16 v[126:129], v[140:143], v[178:181], v[126:129]
	v_mfma_f32_16x16x32_bf16 v[122:125], v[154:157], v[178:181], v[122:125]
	v_mfma_f32_16x16x32_bf16 v[118:121], v[140:143], v[186:189], v[118:121]
	v_mfma_f32_16x16x32_bf16 v[114:117], v[154:157], v[186:189], v[114:117]
	v_mfma_f32_16x16x32_bf16 v[110:113], v[140:143], v[208:211], v[110:113]
	v_mfma_f32_16x16x32_bf16 v[106:109], v[154:157], v[208:211], v[106:109]
	v_mfma_f32_16x16x32_bf16 v[102:105], v[140:143], v[216:219], v[102:105]
	v_mfma_f32_16x16x32_bf16 v[98:101], v[154:157], v[216:219], v[98:101]
	v_mfma_f32_16x16x32_bf16 v[126:129], v[150:153], v[182:185], v[126:129]
	v_mfma_f32_16x16x32_bf16 v[122:125], v[158:161], v[182:185], v[122:125]
	v_mfma_f32_16x16x32_bf16 v[118:121], v[150:153], v[190:193], v[118:121]
	v_mfma_f32_16x16x32_bf16 v[114:117], v[158:161], v[190:193], v[114:117]
	v_mfma_f32_16x16x32_bf16 v[110:113], v[150:153], v[212:215], v[110:113]
	v_mfma_f32_16x16x32_bf16 v[106:109], v[158:161], v[212:215], v[106:109]
	v_mfma_f32_16x16x32_bf16 v[102:105], v[150:153], v[220:223], v[102:105]
	v_mfma_f32_16x16x32_bf16 v[98:101], v[158:161], v[220:223], v[98:101]
	s_setprio 0
	s_setprio 1
	v_mfma_f32_16x16x32_bf16 v[94:97], v[162:165], v[178:181], v[94:97]
	v_mfma_f32_16x16x32_bf16 v[90:93], v[170:173], v[178:181], v[90:93]
	v_mfma_f32_16x16x32_bf16 v[86:89], v[162:165], v[186:189], v[86:89]
	v_mfma_f32_16x16x32_bf16 v[82:85], v[170:173], v[186:189], v[82:85]
	v_mfma_f32_16x16x32_bf16 v[78:81], v[162:165], v[208:211], v[78:81]
	v_mfma_f32_16x16x32_bf16 v[74:77], v[170:173], v[208:211], v[74:77]
	v_mfma_f32_16x16x32_bf16 v[70:73], v[162:165], v[216:219], v[70:73]
	v_mfma_f32_16x16x32_bf16 v[66:69], v[170:173], v[216:219], v[66:69]
	v_mfma_f32_16x16x32_bf16 v[94:97], v[166:169], v[182:185], v[94:97]
	v_mfma_f32_16x16x32_bf16 v[90:93], v[174:177], v[182:185], v[90:93]
	v_mfma_f32_16x16x32_bf16 v[86:89], v[166:169], v[190:193], v[86:89]
	v_mfma_f32_16x16x32_bf16 v[82:85], v[174:177], v[190:193], v[82:85]
	v_mfma_f32_16x16x32_bf16 v[78:81], v[166:169], v[212:215], v[78:81]
	v_mfma_f32_16x16x32_bf16 v[74:77], v[174:177], v[212:215], v[74:77]
	v_mfma_f32_16x16x32_bf16 v[70:73], v[166:169], v[220:223], v[70:73]
	v_mfma_f32_16x16x32_bf16 v[66:69], v[174:177], v[220:223], v[66:69]
	s_setprio 0
	s_barrier
; #define PG8_STAGE(bufoff, gbase, voff) do { _Pragma("unroll") for (int _i = 0; _i < 2; ++_i) \
;         __builtin_amdgcn_global_load_lds((const unsigned*)((const char*)(gbase) + (voff)[_i]), (PG8_LAS unsigned*)(lds + (bufoff) + ldsw + _i * 8192), 16, 0, 0); } while (0)
; #define PG8_STAGEA(bufoff, gbase, voff) do { _Pragma("unroll") for (int _i = 0; _i < 2; ++_i) \
;         __builtin_amdgcn_global_load_lds((const unsigned*)((const char*)(gbase) + (voff)[_i]), (PG8_LAS unsigned*)(lds + (bufoff) + ldsw + _i * 8192), 16, 0, A_SC1 ? 16 : 0); } while (0)
; #define PG8_LDA(dst, b, h) do { _Pragma("unroll") for (int m = 0; m < 4; ++m) _Pragma("unroll") for (int k = 0; k < 2; ++k) dst[m][k] = *(const PG8_LAS bf16x8*)(lds + PG8_SA(b, h) + aoff + m * 2048 + k * 1024); } while (0)
; #define PG8_MMA(ai, bj, At, Bt) do { __builtin_amdgcn_s_setprio(1); _Pragma("unroll") for (int m = 0; m < 4; ++m) _Pragma("unroll") for (int n = 0; n < 2; ++n) _Pragma("unroll") for (int k = 0; k < 2; ++k) \
;         acc[ai][bj][m][n] = __builtin_amdgcn_mfma_f32_16x16x32_bf16(Bt[n][k], At[m][k], acc[ai][bj][m][n], 0, 0, 0); __builtin_amdgcn_s_setprio(0); } while (0)
; #define PG8_WAIT_V(n) asm volatile("s_waitcnt vmcnt(" #n ")" ::: "memory")
; #define PG8_BAR __builtin_amdgcn_s_barrier()
;     __device__ __forceinline__ void operator()(const f32x4 (&acc)[2][2][4][2], const Unit& u, int wr, int wc, int fr, int fq) const {
;     ...
;         for (int n = 0; n < 2; ++n) { b0[n] = (MODE == 1) ? *(const f32x4*)(bias + col0 + 4 * n) : (f32x4){0.f, 0.f, 0.f, 0.f}; b1[n] = (MODE == 1) ? *(const f32x4*)(bias + nh + col0 + 4 * n) : (f32x4){0.f, 0.f, 0.f, 0.f}; }
;         float rsv[2][4];
; #pragma unroll
;         for (int ai = 0; ai < 2; ++ai)
; #pragma unroll
;             for (int m = 0; m < 4; ++m) rsv[ai][m] = ld_f32_ag(ss + row0 + ai * HALF + m * 16);
;         publish_prev(pendp, lane, rsv[1][3]);
; template <class Epi, class Sched, bool ALIGN_EPI = false, bool SP2 = false, bool A_SC1 = false>
; __device__ __forceinline__ void gemm_phase(PG8_LAS unsigned char* lds, const Gemm g, const Sched& S, const Epi& E, const int tid) {
;     ...
;             PG8_LDA(At, 1, 1); PG8_STAGE(PG8_SB(1, 0), b3, voffB); PG8_STAGE(PG8_SB(1, 1), b3 + hstep, voffB); PG8_STAGEA(PG8_SA(1, 0), a3, voffA);
;             PG8_WAIT_V(8); PG8_WAIT_L(0); PG8_BAR; PG8_MMA(1, 0, At, B0); PG8_MMA(1, 1, At, B1); PG8_BAR; PG8_SCHED;
	s_add_i32 s36, s36, s3
	v_lshl_add_u64 v[144:145], v[144:145], 0, s[34:35]
	s_mov_b32 m0, s36
	ds_read_b128 v[178:181], v148 offset:49152
	ds_read_b128 v[182:185], v148 offset:50176
	ds_read_b128 v[186:189], v148 offset:51200
	ds_read_b128 v[190:193], v148 offset:52224
	ds_read_b128 v[208:211], v148 offset:53248
	ds_read_b128 v[212:215], v148 offset:54272
	ds_read_b128 v[216:219], v148 offset:55296
	ds_read_b128 v[220:223], v148 offset:56320
	global_load_lds_dwordx4 v[144:145], off
	s_add_i32 m0, s36, 0x2000
	s_add_u32 s38, s38, 0x40080
	v_lshl_add_u64 v[144:145], v[224:225], 0, s[34:35]
	s_addc_u32 s39, s39, 0
	s_add_i32 s36, s37, s3
	global_load_lds_dwordx4 v[144:145], off
	v_lshl_add_u64 v[144:145], s[38:39], 0, v[132:133]
	s_mov_b32 m0, s36
	s_nop 0
	global_load_lds_dwordx4 v[144:145], off
	v_lshl_add_u64 v[144:145], s[38:39], 0, v[136:137]
	s_add_i32 m0, s36, 0x2000
	s_nop 0
	global_load_lds_dwordx4 v[144:145], off
	v_lshl_add_u64 v[144:145], v[226:227], 0, s[34:35]
	s_mov_b32 m0, s66
	s_nop 0
	global_load_lds_dwordx4 v[144:145], off
	v_lshl_add_u64 v[144:145], v[228:229], 0, s[34:35]
	s_mov_b32 m0, s67
	s_nop 0
	global_load_lds_dwordx4 v[144:145], off
	s_waitcnt vmcnt(8)
	s_waitcnt lgkmcnt(0)
	s_cmp_lg_u32 s85, 14
	s_cbranch_scc1 .Lglu_nopf
	v_lshl_add_u32 v236, s2, 8, v1
	v_ashrrev_i32_e32 v237, 31, v236
	v_lshl_add_u64 v[236:237], v[236:237], 2, s[14:15]
	global_load_dword v244, v[236:237], off
	global_load_dword v245, v[236:237], off offset:64
	global_load_dword v251, v[236:237], off offset:704
	global_load_dword v246, v[236:237], off offset:128
	global_load_dword v247, v[236:237], off offset:192
	global_load_dword v248, v[236:237], off offset:512
	global_load_dword v249, v[236:237], off offset:576
	global_load_dword v250, v[236:237], off offset:640
.Lglu_nopf:
	s_barrier
	s_setprio 1
	s_waitcnt lgkmcnt(0)
	v_mfma_f32_16x16x32_bf16 v[62:65], v[140:143], v[178:181], v[62:65]
	v_mfma_f32_16x16x32_bf16 v[58:61], v[154:157], v[178:181], v[58:61]
	v_mfma_f32_16x16x32_bf16 v[54:57], v[140:143], v[186:189], v[54:57]
	v_mfma_f32_16x16x32_bf16 v[50:53], v[154:157], v[186:189], v[50:53]
	v_mfma_f32_16x16x32_bf16 v[46:49], v[140:143], v[208:211], v[46:49]
	v_mfma_f32_16x16x32_bf16 v[42:45], v[154:157], v[208:211], v[42:45]
	v_mfma_f32_16x16x32_bf16 v[38:41], v[140:143], v[216:219], v[38:41]
	v_mfma_f32_16x16x32_bf16 v[34:37], v[154:157], v[216:219], v[34:37]
	v_mfma_f32_16x16x32_bf16 v[62:65], v[150:153], v[182:185], v[62:65]
	v_mfma_f32_16x16x32_bf16 v[58:61], v[158:161], v[182:185], v[58:61]
	v_mfma_f32_16x16x32_bf16 v[54:57], v[150:153], v[190:193], v[54:57]
	v_mfma_f32_16x16x32_bf16 v[50:53], v[158:161], v[190:193], v[50:53]
	v_mfma_f32_16x16x32_bf16 v[46:49], v[150:153], v[212:215], v[46:49]
	v_mfma_f32_16x16x32_bf16 v[42:45], v[158:161], v[212:215], v[42:45]
	v_mfma_f32_16x16x32_bf16 v[38:41], v[150:153], v[220:223], v[38:41]
	v_mfma_f32_16x16x32_bf16 v[34:37], v[158:161], v[220:223], v[34:37]
	s_setprio 0
	s_setprio 1
	v_mfma_f32_16x16x32_bf16 v[30:33], v[162:165], v[178:181], v[30:33]
	v_mfma_f32_16x16x32_bf16 v[26:29], v[170:173], v[178:181], v[26:29]
	v_mfma_f32_16x16x32_bf16 v[22:25], v[162:165], v[186:189], v[22:25]
	v_mfma_f32_16x16x32_bf16 v[18:21], v[170:173], v[186:189], v[18:21]
	v_mfma_f32_16x16x32_bf16 v[14:17], v[162:165], v[208:211], v[14:17]
	v_mfma_f32_16x16x32_bf16 v[10:13], v[170:173], v[208:211], v[10:13]
	v_mfma_f32_16x16x32_bf16 v[6:9], v[162:165], v[216:219], v[6:9]
	v_mfma_f32_16x16x32_bf16 v[2:5], v[170:173], v[216:219], v[2:5]
	v_mfma_f32_16x16x32_bf16 v[30:33], v[166:169], v[182:185], v[30:33]
	v_mfma_f32_16x16x32_bf16 v[26:29], v[174:177], v[182:185], v[26:29]
	v_mfma_f32_16x16x32_bf16 v[22:25], v[166:169], v[190:193], v[22:25]
	v_mfma_f32_16x16x32_bf16 v[18:21], v[174:177], v[190:193], v[18:21]
	v_mfma_f32_16x16x32_bf16 v[14:17], v[166:169], v[212:215], v[14:17]
	v_mfma_f32_16x16x32_bf16 v[10:13], v[174:177], v[212:215], v[10:13]
	v_mfma_f32_16x16x32_bf16 v[6:9], v[166:169], v[220:223], v[6:9]
	v_mfma_f32_16x16x32_bf16 v[2:5], v[174:177], v[220:223], v[2:5]
	s_setprio 0
	s_barrier
	s_add_i32 s38, s85, 2
	s_cmp_gt_u32 s85, 13
	s_cbranch_scc0 .LBB0_751
	s_and_b64 vcc, exec, s[16:17]
	s_cbranch_vccz .LBB0_783
	s_barrier
.LBB0_783:
	v_lshl_add_u32 v140, s2, 8, v1
	v_ashrrev_i32_e32 v141, 31, v140
	s_waitcnt vmcnt(0)
	v_lshl_add_u64 v[138:139], v[140:141], 2, s[14:15]
	v_mov_b32_e32 v142, v244
	v_mov_b32_e32 v154, v245
	v_mov_b32_e32 v141, v251
	v_mov_b32_e32 v153, v246
	v_mov_b32_e32 v152, v247
	v_mov_b32_e32 v151, v248
	v_mov_b32_e32 v150, v249
	v_mov_b32_e32 v149, v250
	v_cmp_eq_u64_e32 vcc, 0, v[206:207]
	s_nor_b64 s[60:61], vcc, s[48:49]
	v_cndmask_b32_e32 v139, 0, v207, vcc
	v_cndmask_b32_e32 v138, 0, v206, vcc
	s_and_saveexec_b64 s[38:39], s[60:61]
	s_cbranch_execz .LBB0_785
	global_atomic_add v[206:207], v231, off
	v_mov_b64_e32 v[138:139], 0
; __device__ __forceinline__ float rs_from_ss(float ss) { return __builtin_amdgcn_rsqf(ss * (1.0f / 1024.0f) + RMS_EPS); }
; __device__ __forceinline__ void st16_wt(void* p, u32x4 v) { asm volatile("global_store_dwordx4 %0, %1, off sc1\n\ts_nop 1" :: "v"(p), "v"(v) : "memory"); }
; __device__ __forceinline__ u32x4 pack8(const f32x4& a, const f32x4& b) { u32x4 w; w.x = cvt_pk_bf16(a[0], a[1]); w.y = cvt_pk_bf16(a[2], a[3]); w.z = cvt_pk_bf16(b[0], b[1]); w.w = cvt_pk_bf16(b[2], b[3]); return w; }
;     __device__ __forceinline__ void operator()(const f32x4 (&acc)[2][2][4][2], const Unit& u, int wr, int wc, int fr, int fq) const {
;     ...
;         publish_prev(pendp, lane, rsv[1][3]);
; #pragma unroll
;         for (int ai = 0; ai < 2; ++ai)
; #pragma unroll
;             for (int m = 0; m < 4; ++m) { const int row = row0 + ai * HALF + m * 16; const float rs = rs_from_ss(rsv[ai][m]); f32x4 o[2];
; #pragma unroll
;                 for (int n = 0; n < 2; ++n) { const f32x4 v0 = acc[ai][0][m][n] * rs + b0[n], v1 = acc[ai][1][m][n] * rs + b1[n];
;                     const f32x4 sx = (MODE == 0) ? v0 : v1, tt = sx * (-LOG2E); f32x4 dd;
; #pragma unroll
;                     for (int i = 0; i < 4; ++i) dd[i] = __builtin_amdgcn_exp2f(tt[i]);
;                     dd = dd + 1.0f;
; #pragma unroll
;                     for (int i = 0; i < 4; ++i) dd[i] = __builtin_amdgcn_rcpf(dd[i]);
;                     o[n] = (MODE == 0) ? (v0 * dd) * v1 : v0 * dd; }
;                 st16_wt(O + (size_t)row * ldc + col0, pack8(o[0], o[1]));
.LBB0_785:
	s_or_b64 exec, exec, s[38:39]
	v_fmamk_f32 v142, v142, 0x3a800000, v232
	v_rsq_f32_e32 v142, v142
	v_fmamk_f32 v154, v154, 0x3a800000, v232
	v_readlane_b32 s36, v255, 13
	v_rsq_f32_e32 v154, v154
	v_pk_fma_f32 v[158:159], v[126:127], v[142:143], 0 op_sel_hi:[1,0,0]
	v_pk_fma_f32 v[156:157], v[128:129], v[142:143], 0 op_sel_hi:[1,0,0]
	v_mul_f32_e32 v143, 0xbfb8aa3b, v158
	v_exp_f32_e32 v160, v143
	v_mul_f32_e32 v143, 0xbfb8aa3b, v159
	v_exp_f32_e32 v161, v143
	v_mul_f32_e32 v143, 0xbfb8aa3b, v156
	v_exp_f32_e32 v162, v143
	v_mul_f32_e32 v143, 0xbfb8aa3b, v157
	v_exp_f32_e32 v163, v143
	v_pk_add_f32 v[160:161], v[160:161], 1.0 op_sel_hi:[1,0]
	v_pk_fma_f32 v[164:165], v[94:95], v[142:143], 0 op_sel_hi:[1,0,0]
	v_rcp_f32_e32 v160, v160
	v_pk_add_f32 v[162:163], v[162:163], 1.0 op_sel_hi:[1,0]
	v_rcp_f32_e32 v161, v161
	v_rcp_f32_e32 v162, v162
	v_rcp_f32_e32 v163, v163
	v_pk_fma_f32 v[166:167], v[96:97], v[142:143], 0 op_sel_hi:[1,0,0]
	v_pk_mul_f32 v[158:159], v[158:159], v[160:161]
	v_lshl_or_b32 v144, s4, 7, v147
	v_pk_mul_f32 v[156:157], v[156:157], v[162:163]
	v_pk_fma_f32 v[162:163], v[122:123], v[142:143], 0 op_sel_hi:[1,0,0]
	v_pk_mul_f32 v[160:161], v[166:167], v[156:157]
	v_pk_mul_f32 v[156:157], v[164:165], v[158:159]
	v_pk_fma_f32 v[158:159], v[124:125], v[142:143], 0 op_sel_hi:[1,0,0]
	v_mul_f32_e32 v143, 0xbfb8aa3b, v162
	v_exp_f32_e32 v164, v143
	v_mul_f32_e32 v143, 0xbfb8aa3b, v163
	v_exp_f32_e32 v165, v143
	v_mul_f32_e32 v143, 0xbfb8aa3b, v158
	v_exp_f32_e32 v166, v143
	v_mul_f32_e32 v143, 0xbfb8aa3b, v159
	v_exp_f32_e32 v167, v143
	v_pk_add_f32 v[164:165], v[164:165], 1.0 op_sel_hi:[1,0]
	v_pk_fma_f32 v[168:169], v[90:91], v[142:143], 0 op_sel_hi:[1,0,0]
	v_rcp_f32_e32 v164, v164
	v_pk_add_f32 v[166:167], v[166:167], 1.0 op_sel_hi:[1,0]
	v_rcp_f32_e32 v165, v165
	v_rcp_f32_e32 v166, v166
	v_rcp_f32_e32 v167, v167
	v_pk_fma_f32 v[142:143], v[92:93], v[142:143], 0 op_sel_hi:[1,0,0]
	v_pk_mul_f32 v[162:163], v[162:163], v[164:165]
	v_readlane_b32 s37, v255, 14
	v_pk_mul_f32 v[158:159], v[158:159], v[166:167]
	v_ashrrev_i32_e32 v145, 31, v144
	v_pk_mul_f32 v[164:165], v[142:143], v[158:159]
	v_pk_mul_f32 v[158:159], v[168:169], v[162:163]
	v_mov_b64_e32 v[142:143], s[36:37]
	s_movk_i32 s36, 0x1600
	v_mad_i64_i32 v[162:163], s[38:39], v140, s36, v[142:143]
	v_lshlrev_b64 v[144:145], 1, v[144:145]
	v_cvt_pk_bf16_f32 v156, v156, v157
	v_cvt_pk_bf16_f32 v157, v160, v161
	v_cvt_pk_bf16_f32 v158, v158, v159
	v_cvt_pk_bf16_f32 v159, v164, v165
	v_lshl_add_u64 v[162:163], v[162:163], 0, v[144:145]
	global_store_dwordx4 v[162:163], v[156:159], off sc1
	s_nop 1
	v_pk_fma_f32 v[158:159], v[118:119], v[154:155], 0 op_sel_hi:[1,0,0]
	v_pk_fma_f32 v[156:157], v[120:121], v[154:155], 0 op_sel_hi:[1,0,0]
	v_mul_f32_e32 v155, 0xbfb8aa3b, v158
	v_exp_f32_e32 v160, v155
	v_mul_f32_e32 v155, 0xbfb8aa3b, v159
	v_exp_f32_e32 v161, v155
	v_mul_f32_e32 v155, 0xbfb8aa3b, v156
	v_exp_f32_e32 v162, v155
	v_mul_f32_e32 v155, 0xbfb8aa3b, v157
	v_exp_f32_e32 v163, v155
	v_pk_add_f32 v[160:161], v[160:161], 1.0 op_sel_hi:[1,0]
	v_pk_fma_f32 v[164:165], v[86:87], v[154:155], 0 op_sel_hi:[1,0,0]
	v_rcp_f32_e32 v160, v160
	v_pk_add_f32 v[162:163], v[162:163], 1.0 op_sel_hi:[1,0]
	v_rcp_f32_e32 v161, v161
	v_rcp_f32_e32 v162, v162
	v_rcp_f32_e32 v163, v163
	v_pk_fma_f32 v[166:167], v[88:89], v[154:155], 0 op_sel_hi:[1,0,0]
	v_pk_mul_f32 v[158:159], v[158:159], v[160:161]
	v_pk_fma_f32 v[160:161], v[116:117], v[154:155], 0 op_sel_hi:[1,0,0]
	v_pk_mul_f32 v[156:157], v[156:157], v[162:163]
	v_pk_fma_f32 v[162:163], v[114:115], v[154:155], 0 op_sel_hi:[1,0,0]
	v_pk_mul_f32 v[158:159], v[164:165], v[158:159]
	v_mul_f32_e32 v155, 0xbfb8aa3b, v162
	v_exp_f32_e32 v164, v155
	v_mul_f32_e32 v155, 0xbfb8aa3b, v163
	v_exp_f32_e32 v165, v155
	v_mul_f32_e32 v155, 0xbfb8aa3b, v160
	v_pk_mul_f32 v[156:157], v[166:167], v[156:157]
	v_exp_f32_e32 v166, v155
	v_mul_f32_e32 v155, 0xbfb8aa3b, v161
	v_exp_f32_e32 v167, v155
	v_pk_add_f32 v[164:165], v[164:165], 1.0 op_sel_hi:[1,0]
	v_pk_fma_f32 v[168:169], v[82:83], v[154:155], 0 op_sel_hi:[1,0,0]
	v_rcp_f32_e32 v164, v164
	v_pk_add_f32 v[166:167], v[166:167], 1.0 op_sel_hi:[1,0]
	v_rcp_f32_e32 v165, v165
	v_rcp_f32_e32 v166, v166
	v_rcp_f32_e32 v167, v167
	v_pk_fma_f32 v[154:155], v[84:85], v[154:155], 0 op_sel_hi:[1,0,0]
	v_pk_mul_f32 v[162:163], v[162:163], v[164:165]
	v_fmamk_f32 v153, v153, 0x3a800000, v232
	v_pk_mul_f32 v[160:161], v[160:161], v[166:167]
	v_pk_mul_f32 v[162:163], v[168:169], v[162:163]
	v_pk_mul_f32 v[160:161], v[154:155], v[160:161]
	v_or_b32_e32 v154, 16, v140
	v_mad_i64_i32 v[154:155], s[38:39], v154, s36, v[142:143]
	v_lshl_add_u64 v[164:165], v[154:155], 0, v[144:145]
	v_cvt_pk_bf16_f32 v154, v158, v159
	v_cvt_pk_bf16_f32 v155, v156, v157
	v_cvt_pk_bf16_f32 v156, v162, v163
	v_cvt_pk_bf16_f32 v157, v160, v161
	v_fmamk_f32 v152, v152, 0x3a800000, v232
	global_store_dwordx4 v[164:165], v[154:157], off sc1
	s_nop 1
	v_rsq_f32_e32 v154, v153
	v_rsq_f32_e32 v152, v152
	v_fmamk_f32 v151, v151, 0x3a800000, v232
	v_fmamk_f32 v150, v150, 0x3a800000, v232
	v_pk_fma_f32 v[158:159], v[110:111], v[154:155], 0 op_sel_hi:[1,0,0]
	v_pk_fma_f32 v[156:157], v[112:113], v[154:155], 0 op_sel_hi:[1,0,0]
	v_mul_f32_e32 v153, 0xbfb8aa3b, v158
	v_exp_f32_e32 v160, v153
	v_mul_f32_e32 v153, 0xbfb8aa3b, v159
	v_exp_f32_e32 v161, v153
	v_mul_f32_e32 v153, 0xbfb8aa3b, v156
	v_exp_f32_e32 v162, v153
	v_mul_f32_e32 v153, 0xbfb8aa3b, v157
	v_exp_f32_e32 v163, v153
	v_pk_add_f32 v[160:161], v[160:161], 1.0 op_sel_hi:[1,0]
	v_pk_fma_f32 v[164:165], v[78:79], v[154:155], 0 op_sel_hi:[1,0,0]
	v_rcp_f32_e32 v160, v160
; __device__ __forceinline__ float rs_from_ss(float ss) { return __builtin_amdgcn_rsqf(ss * (1.0f / 1024.0f) + RMS_EPS); }
; __device__ __forceinline__ void st16_wt(void* p, u32x4 v) { asm volatile("global_store_dwordx4 %0, %1, off sc1\n\ts_nop 1" :: "v"(p), "v"(v) : "memory"); }
; __device__ __forceinline__ u32x4 pack8(const f32x4& a, const f32x4& b) { u32x4 w; w.x = cvt_pk_bf16(a[0], a[1]); w.y = cvt_pk_bf16(a[2], a[3]); w.z = cvt_pk_bf16(b[0], b[1]); w.w = cvt_pk_bf16(b[2], b[3]); return w; }
;     __device__ __forceinline__ void operator()(const f32x4 (&acc)[2][2][4][2], const Unit& u, int wr, int wc, int fr, int fq) const {
;     ...
;         for (int ai = 0; ai < 2; ++ai)
; #pragma unroll
;             for (int m = 0; m < 4; ++m) { const int row = row0 + ai * HALF + m * 16; const float rs = rs_from_ss(rsv[ai][m]); f32x4 o[2];
; #pragma unroll
;                 for (int n = 0; n < 2; ++n) { const f32x4 v0 = acc[ai][0][m][n] * rs + b0[n], v1 = acc[ai][1][m][n] * rs + b1[n];
;                     const f32x4 sx = (MODE == 0) ? v0 : v1, tt = sx * (-LOG2E); f32x4 dd;
; #pragma unroll
;                     for (int i = 0; i < 4; ++i) dd[i] = __builtin_amdgcn_exp2f(tt[i]);
;                     dd = dd + 1.0f;
; #pragma unroll
;                     for (int i = 0; i < 4; ++i) dd[i] = __builtin_amdgcn_rcpf(dd[i]);
;                     o[n] = (MODE == 0) ? (v0 * dd) * v1 : v0 * dd; }
;                 st16_wt(O + (size_t)row * ldc + col0, pack8(o[0], o[1]));
	v_pk_add_f32 v[162:163], v[162:163], 1.0 op_sel_hi:[1,0]
	v_rcp_f32_e32 v161, v161
	v_rcp_f32_e32 v162, v162
	v_rcp_f32_e32 v163, v163
	v_pk_fma_f32 v[166:167], v[80:81], v[154:155], 0 op_sel_hi:[1,0,0]
	v_pk_mul_f32 v[158:159], v[158:159], v[160:161]
	v_pk_fma_f32 v[160:161], v[108:109], v[154:155], 0 op_sel_hi:[1,0,0]
	v_pk_mul_f32 v[156:157], v[156:157], v[162:163]
	v_pk_fma_f32 v[162:163], v[106:107], v[154:155], 0 op_sel_hi:[1,0,0]
	v_pk_mul_f32 v[158:159], v[164:165], v[158:159]
	v_mul_f32_e32 v153, 0xbfb8aa3b, v162
	v_exp_f32_e32 v164, v153
	v_mul_f32_e32 v153, 0xbfb8aa3b, v163
	v_exp_f32_e32 v165, v153
	v_mul_f32_e32 v153, 0xbfb8aa3b, v160
	v_pk_mul_f32 v[156:157], v[166:167], v[156:157]
	v_exp_f32_e32 v166, v153
	v_mul_f32_e32 v153, 0xbfb8aa3b, v161
	v_exp_f32_e32 v167, v153
	v_pk_add_f32 v[164:165], v[164:165], 1.0 op_sel_hi:[1,0]
	v_pk_fma_f32 v[168:169], v[74:75], v[154:155], 0 op_sel_hi:[1,0,0]
	v_rcp_f32_e32 v164, v164
	v_pk_add_f32 v[166:167], v[166:167], 1.0 op_sel_hi:[1,0]
	v_rcp_f32_e32 v165, v165
	v_rcp_f32_e32 v166, v166
	v_rcp_f32_e32 v167, v167
	v_pk_fma_f32 v[154:155], v[76:77], v[154:155], 0 op_sel_hi:[1,0,0]
	v_or_b32_e32 v153, 32, v140
	v_pk_mul_f32 v[162:163], v[162:163], v[164:165]
	v_pk_mul_f32 v[160:161], v[160:161], v[166:167]
	v_pk_mul_f32 v[162:163], v[168:169], v[162:163]
	v_pk_mul_f32 v[160:161], v[154:155], v[160:161]
	v_mad_i64_i32 v[154:155], s[38:39], v153, s36, v[142:143]
	v_lshl_add_u64 v[164:165], v[154:155], 0, v[144:145]
	v_cvt_pk_bf16_f32 v154, v158, v159
	v_cvt_pk_bf16_f32 v155, v156, v157
	v_cvt_pk_bf16_f32 v156, v162, v163
	v_cvt_pk_bf16_f32 v157, v160, v161
	v_rsq_f32_e32 v150, v150
	global_store_dwordx4 v[164:165], v[154:157], off sc1
	s_nop 1
	v_pk_fma_f32 v[156:157], v[102:103], v[152:153], 0 op_sel_hi:[1,0,0]
	v_pk_fma_f32 v[154:155], v[104:105], v[152:153], 0 op_sel_hi:[1,0,0]
	v_mul_f32_e32 v153, 0xbfb8aa3b, v156
	v_exp_f32_e32 v158, v153
	v_mul_f32_e32 v153, 0xbfb8aa3b, v157
	v_exp_f32_e32 v159, v153
	v_mul_f32_e32 v153, 0xbfb8aa3b, v154
	v_exp_f32_e32 v160, v153
	v_mul_f32_e32 v153, 0xbfb8aa3b, v155
	v_exp_f32_e32 v161, v153
	v_pk_add_f32 v[158:159], v[158:159], 1.0 op_sel_hi:[1,0]
	v_pk_fma_f32 v[162:163], v[70:71], v[152:153], 0 op_sel_hi:[1,0,0]
	v_rcp_f32_e32 v158, v158
	v_pk_add_f32 v[160:161], v[160:161], 1.0 op_sel_hi:[1,0]
	v_rcp_f32_e32 v159, v159
	v_rcp_f32_e32 v160, v160
	v_rcp_f32_e32 v161, v161
	v_pk_fma_f32 v[164:165], v[72:73], v[152:153], 0 op_sel_hi:[1,0,0]
	v_pk_mul_f32 v[156:157], v[156:157], v[158:159]
	v_pk_fma_f32 v[158:159], v[100:101], v[152:153], 0 op_sel_hi:[1,0,0]
	v_pk_mul_f32 v[154:155], v[154:155], v[160:161]
	v_pk_fma_f32 v[160:161], v[98:99], v[152:153], 0 op_sel_hi:[1,0,0]
	v_pk_mul_f32 v[156:157], v[162:163], v[156:157]
	v_mul_f32_e32 v153, 0xbfb8aa3b, v160
	v_exp_f32_e32 v162, v153
	v_mul_f32_e32 v153, 0xbfb8aa3b, v161
	v_exp_f32_e32 v163, v153
	v_mul_f32_e32 v153, 0xbfb8aa3b, v158
	v_pk_mul_f32 v[154:155], v[164:165], v[154:155]
	v_exp_f32_e32 v164, v153
	v_mul_f32_e32 v153, 0xbfb8aa3b, v159
	v_exp_f32_e32 v165, v153
	v_pk_add_f32 v[162:163], v[162:163], 1.0 op_sel_hi:[1,0]
	v_pk_fma_f32 v[166:167], v[66:67], v[152:153], 0 op_sel_hi:[1,0,0]
	v_rcp_f32_e32 v162, v162
	v_pk_add_f32 v[164:165], v[164:165], 1.0 op_sel_hi:[1,0]
	v_rcp_f32_e32 v163, v163
	v_rcp_f32_e32 v164, v164
	v_rcp_f32_e32 v165, v165
	v_pk_fma_f32 v[152:153], v[68:69], v[152:153], 0 op_sel_hi:[1,0,0]
	v_pk_mul_f32 v[160:161], v[160:161], v[162:163]
	v_add_u32_e32 v168, 0x80, v140
	v_pk_mul_f32 v[158:159], v[158:159], v[164:165]
	v_pk_mul_f32 v[160:161], v[166:167], v[160:161]
	v_pk_mul_f32 v[158:159], v[152:153], v[158:159]
	v_or_b32_e32 v152, 48, v140
	v_mad_i64_i32 v[152:153], s[38:39], v152, s36, v[142:143]
	v_lshl_add_u64 v[162:163], v[152:153], 0, v[144:145]
	v_cvt_pk_bf16_f32 v152, v156, v157
	v_cvt_pk_bf16_f32 v153, v154, v155
	v_cvt_pk_bf16_f32 v154, v160, v161
	v_cvt_pk_bf16_f32 v155, v158, v159
	v_fmamk_f32 v149, v149, 0x3a800000, v232
	global_store_dwordx4 v[162:163], v[152:155], off sc1
	s_nop 1
	v_rsq_f32_e32 v152, v151
	v_fmamk_f32 v141, v141, 0x3a800000, v232
	s_mov_b64 s[60:61], -1
	v_pk_fma_f32 v[156:157], v[62:63], v[152:153], 0 op_sel_hi:[1,0,0]
	s_nop 0
	v_mul_f32_e32 v151, 0xbfb8aa3b, v156
	v_pk_fma_f32 v[154:155], v[64:65], v[152:153], 0 op_sel_hi:[1,0,0]
	v_exp_f32_e32 v158, v151
	v_mul_f32_e32 v151, 0xbfb8aa3b, v157
	v_exp_f32_e32 v159, v151
	v_mul_f32_e32 v151, 0xbfb8aa3b, v154
	v_exp_f32_e32 v160, v151
	v_mul_f32_e32 v151, 0xbfb8aa3b, v155
	v_exp_f32_e32 v161, v151
	v_pk_add_f32 v[158:159], v[158:159], 1.0 op_sel_hi:[1,0]
	v_pk_fma_f32 v[162:163], v[30:31], v[152:153], 0 op_sel_hi:[1,0,0]
	v_rcp_f32_e32 v158, v158
	v_pk_add_f32 v[160:161], v[160:161], 1.0 op_sel_hi:[1,0]
	v_rcp_f32_e32 v159, v159
	v_rcp_f32_e32 v160, v160
	v_rcp_f32_e32 v161, v161
	v_pk_fma_f32 v[164:165], v[32:33], v[152:153], 0 op_sel_hi:[1,0,0]
	v_pk_mul_f32 v[156:157], v[156:157], v[158:159]
	v_pk_fma_f32 v[158:159], v[60:61], v[152:153], 0 op_sel_hi:[1,0,0]
	v_pk_mul_f32 v[154:155], v[154:155], v[160:161]
	v_pk_fma_f32 v[160:161], v[58:59], v[152:153], 0 op_sel_hi:[1,0,0]
	v_pk_mul_f32 v[156:157], v[162:163], v[156:157]
	v_mul_f32_e32 v151, 0xbfb8aa3b, v160
	v_exp_f32_e32 v162, v151
	v_mul_f32_e32 v151, 0xbfb8aa3b, v161
	v_exp_f32_e32 v163, v151
	v_mul_f32_e32 v151, 0xbfb8aa3b, v158
	v_pk_mul_f32 v[154:155], v[164:165], v[154:155]
	v_exp_f32_e32 v164, v151
	v_mul_f32_e32 v151, 0xbfb8aa3b, v159
	v_exp_f32_e32 v165, v151
	v_pk_add_f32 v[162:163], v[162:163], 1.0 op_sel_hi:[1,0]
	v_pk_fma_f32 v[166:167], v[26:27], v[152:153], 0 op_sel_hi:[1,0,0]
	v_rcp_f32_e32 v162, v162
; __device__ __forceinline__ float rs_from_ss(float ss) { return __builtin_amdgcn_rsqf(ss * (1.0f / 1024.0f) + RMS_EPS); }
; __device__ __forceinline__ void st16_wt(void* p, u32x4 v) { asm volatile("global_store_dwordx4 %0, %1, off sc1\n\ts_nop 1" :: "v"(p), "v"(v) : "memory"); }
; __device__ __forceinline__ u32x4 pack8(const f32x4& a, const f32x4& b) { u32x4 w; w.x = cvt_pk_bf16(a[0], a[1]); w.y = cvt_pk_bf16(a[2], a[3]); w.z = cvt_pk_bf16(b[0], b[1]); w.w = cvt_pk_bf16(b[2], b[3]); return w; }
;     __device__ __forceinline__ void operator()(const f32x4 (&acc)[2][2][4][2], const Unit& u, int wr, int wc, int fr, int fq) const {
;     ...
;         for (int ai = 0; ai < 2; ++ai)
; #pragma unroll
;             for (int m = 0; m < 4; ++m) { const int row = row0 + ai * HALF + m * 16; const float rs = rs_from_ss(rsv[ai][m]); f32x4 o[2];
; #pragma unroll
;                 for (int n = 0; n < 2; ++n) { const f32x4 v0 = acc[ai][0][m][n] * rs + b0[n], v1 = acc[ai][1][m][n] * rs + b1[n];
;                     const f32x4 sx = (MODE == 0) ? v0 : v1, tt = sx * (-LOG2E); f32x4 dd;
; #pragma unroll
;                     for (int i = 0; i < 4; ++i) dd[i] = __builtin_amdgcn_exp2f(tt[i]);
;                     dd = dd + 1.0f;
; #pragma unroll
;                     for (int i = 0; i < 4; ++i) dd[i] = __builtin_amdgcn_rcpf(dd[i]);
;                     o[n] = (MODE == 0) ? (v0 * dd) * v1 : v0 * dd; }
;                 st16_wt(O + (size_t)row * ldc + col0, pack8(o[0], o[1]));
	v_pk_add_f32 v[164:165], v[164:165], 1.0 op_sel_hi:[1,0]
	v_rcp_f32_e32 v163, v163
	v_rcp_f32_e32 v164, v164
	v_rcp_f32_e32 v165, v165
	v_pk_fma_f32 v[152:153], v[28:29], v[152:153], 0 op_sel_hi:[1,0,0]
	v_pk_mul_f32 v[160:161], v[160:161], v[162:163]
	v_pk_mul_f32 v[158:159], v[158:159], v[164:165]
	s_nop 0
	v_pk_mul_f32 v[158:159], v[152:153], v[158:159]
	v_mad_i64_i32 v[152:153], s[38:39], v168, s36, v[142:143]
	v_pk_mul_f32 v[160:161], v[166:167], v[160:161]
	v_lshl_add_u64 v[162:163], v[152:153], 0, v[144:145]
	v_cvt_pk_bf16_f32 v152, v156, v157
	v_cvt_pk_bf16_f32 v153, v154, v155
	v_cvt_pk_bf16_f32 v154, v160, v161
	v_cvt_pk_bf16_f32 v155, v158, v159
	s_nop 0
	global_store_dwordx4 v[162:163], v[152:155], off sc1
	s_nop 1
	v_pk_fma_f32 v[154:155], v[54:55], v[150:151], 0 op_sel_hi:[1,0,0]
	v_pk_fma_f32 v[152:153], v[56:57], v[150:151], 0 op_sel_hi:[1,0,0]
	v_mul_f32_e32 v151, 0xbfb8aa3b, v154
	v_exp_f32_e32 v156, v151
	v_mul_f32_e32 v151, 0xbfb8aa3b, v155
	v_exp_f32_e32 v157, v151
	v_mul_f32_e32 v151, 0xbfb8aa3b, v152
	v_exp_f32_e32 v158, v151
	v_mul_f32_e32 v151, 0xbfb8aa3b, v153
	v_exp_f32_e32 v159, v151
	v_pk_add_f32 v[156:157], v[156:157], 1.0 op_sel_hi:[1,0]
	v_pk_fma_f32 v[160:161], v[22:23], v[150:151], 0 op_sel_hi:[1,0,0]
	v_rcp_f32_e32 v156, v156
	v_pk_add_f32 v[158:159], v[158:159], 1.0 op_sel_hi:[1,0]
	v_rcp_f32_e32 v157, v157
	v_rcp_f32_e32 v158, v158
	v_rcp_f32_e32 v159, v159
	v_pk_fma_f32 v[162:163], v[24:25], v[150:151], 0 op_sel_hi:[1,0,0]
	v_pk_mul_f32 v[154:155], v[154:155], v[156:157]
	v_pk_fma_f32 v[156:157], v[52:53], v[150:151], 0 op_sel_hi:[1,0,0]
	v_pk_mul_f32 v[152:153], v[152:153], v[158:159]
	v_pk_fma_f32 v[158:159], v[50:51], v[150:151], 0 op_sel_hi:[1,0,0]
	v_pk_mul_f32 v[154:155], v[160:161], v[154:155]
	v_mul_f32_e32 v151, 0xbfb8aa3b, v158
	v_exp_f32_e32 v160, v151
	v_mul_f32_e32 v151, 0xbfb8aa3b, v159
	v_exp_f32_e32 v161, v151
	v_mul_f32_e32 v151, 0xbfb8aa3b, v156
	v_pk_mul_f32 v[152:153], v[162:163], v[152:153]
	v_exp_f32_e32 v162, v151
	v_mul_f32_e32 v151, 0xbfb8aa3b, v157
	v_exp_f32_e32 v163, v151
	v_pk_add_f32 v[160:161], v[160:161], 1.0 op_sel_hi:[1,0]
	v_pk_fma_f32 v[164:165], v[18:19], v[150:151], 0 op_sel_hi:[1,0,0]
	v_rcp_f32_e32 v160, v160
	v_pk_add_f32 v[162:163], v[162:163], 1.0 op_sel_hi:[1,0]
	v_rcp_f32_e32 v161, v161
	v_rcp_f32_e32 v162, v162
	v_rcp_f32_e32 v163, v163
	v_pk_fma_f32 v[150:151], v[20:21], v[150:151], 0 op_sel_hi:[1,0,0]
	v_pk_mul_f32 v[158:159], v[158:159], v[160:161]
	v_pk_mul_f32 v[156:157], v[156:157], v[162:163]
	s_nop 0
	v_pk_mul_f32 v[156:157], v[150:151], v[156:157]
	v_add_u32_e32 v150, 0x90, v140
	v_mad_i64_i32 v[150:151], s[38:39], v150, s36, v[142:143]
	v_lshl_add_u64 v[160:161], v[150:151], 0, v[144:145]
	v_cvt_pk_bf16_f32 v150, v154, v155
	v_pk_mul_f32 v[158:159], v[164:165], v[158:159]
	v_cvt_pk_bf16_f32 v151, v152, v153
	s_nop 0
	v_cvt_pk_bf16_f32 v152, v158, v159
	v_cvt_pk_bf16_f32 v153, v156, v157
	s_nop 0
	global_store_dwordx4 v[160:161], v[150:153], off sc1
	s_nop 1
	v_rsq_f32_e32 v150, v149
	s_nop 0
	v_pk_fma_f32 v[154:155], v[46:47], v[150:151], 0 op_sel_hi:[1,0,0]
	s_nop 0
	v_mul_f32_e32 v149, 0xbfb8aa3b, v154
	v_pk_fma_f32 v[152:153], v[48:49], v[150:151], 0 op_sel_hi:[1,0,0]
	v_exp_f32_e32 v156, v149
	v_mul_f32_e32 v149, 0xbfb8aa3b, v155
	v_exp_f32_e32 v157, v149
	v_mul_f32_e32 v149, 0xbfb8aa3b, v152
	v_exp_f32_e32 v158, v149
	v_mul_f32_e32 v149, 0xbfb8aa3b, v153
	v_exp_f32_e32 v159, v149
	v_pk_add_f32 v[156:157], v[156:157], 1.0 op_sel_hi:[1,0]
	v_pk_fma_f32 v[160:161], v[14:15], v[150:151], 0 op_sel_hi:[1,0,0]
	v_rcp_f32_e32 v156, v156
	v_pk_add_f32 v[158:159], v[158:159], 1.0 op_sel_hi:[1,0]
	v_rcp_f32_e32 v157, v157
	v_rcp_f32_e32 v158, v158
	v_rcp_f32_e32 v159, v159
	v_pk_fma_f32 v[162:163], v[16:17], v[150:151], 0 op_sel_hi:[1,0,0]
	v_pk_mul_f32 v[154:155], v[154:155], v[156:157]
	v_pk_fma_f32 v[156:157], v[44:45], v[150:151], 0 op_sel_hi:[1,0,0]
	v_pk_mul_f32 v[152:153], v[152:153], v[158:159]
;     __device__ __forceinline__ void flush() const { if (*pendp) { asm volatile("s_waitcnt vmcnt(0)" ::: "memory"); publish(*pendp); *pendp = nullptr; } }
; __device__ __forceinline__ float rs_from_ss(float ss) { return __builtin_amdgcn_rsqf(ss * (1.0f / 1024.0f) + RMS_EPS); }
; __device__ __forceinline__ void st16_wt(void* p, u32x4 v) { asm volatile("global_store_dwordx4 %0, %1, off sc1\n\ts_nop 1" :: "v"(p), "v"(v) : "memory"); }
; __device__ __forceinline__ u32x4 pack8(const f32x4& a, const f32x4& b) { u32x4 w; w.x = cvt_pk_bf16(a[0], a[1]); w.y = cvt_pk_bf16(a[2], a[3]); w.z = cvt_pk_bf16(b[0], b[1]); w.w = cvt_pk_bf16(b[2], b[3]); return w; }
;     __device__ __forceinline__ void done(const Unit& u, bool has_next) const {
;         unsigned* m = mine ? mine + 16 * u.pm : nullptr;
;         if (has_next) { flush(); *pendp = m; }
;     __device__ __forceinline__ void operator()(const f32x4 (&acc)[2][2][4][2], const Unit& u, int wr, int wc, int fr, int fq) const {
;     ...
;         for (int ai = 0; ai < 2; ++ai)
; #pragma unroll
;             for (int m = 0; m < 4; ++m) { const int row = row0 + ai * HALF + m * 16; const float rs = rs_from_ss(rsv[ai][m]); f32x4 o[2];
; #pragma unroll
;                 for (int n = 0; n < 2; ++n) { const f32x4 v0 = acc[ai][0][m][n] * rs + b0[n], v1 = acc[ai][1][m][n] * rs + b1[n];
;                     const f32x4 sx = (MODE == 0) ? v0 : v1, tt = sx * (-LOG2E); f32x4 dd;
; #pragma unroll
;                     for (int i = 0; i < 4; ++i) dd[i] = __builtin_amdgcn_exp2f(tt[i]);
;                     dd = dd + 1.0f;
; #pragma unroll
;                     for (int i = 0; i < 4; ++i) dd[i] = __builtin_amdgcn_rcpf(dd[i]);
;                     o[n] = (MODE == 0) ? (v0 * dd) * v1 : v0 * dd; }
;                 st16_wt(O + (size_t)row * ldc + col0, pack8(o[0], o[1]));
	v_pk_fma_f32 v[158:159], v[42:43], v[150:151], 0 op_sel_hi:[1,0,0]
	v_pk_mul_f32 v[154:155], v[160:161], v[154:155]
	v_mul_f32_e32 v149, 0xbfb8aa3b, v158
	v_exp_f32_e32 v160, v149
	v_mul_f32_e32 v149, 0xbfb8aa3b, v159
	v_exp_f32_e32 v161, v149
	v_mul_f32_e32 v149, 0xbfb8aa3b, v156
	v_pk_mul_f32 v[152:153], v[162:163], v[152:153]
	v_exp_f32_e32 v162, v149
	v_mul_f32_e32 v149, 0xbfb8aa3b, v157
	v_exp_f32_e32 v163, v149
	v_pk_add_f32 v[160:161], v[160:161], 1.0 op_sel_hi:[1,0]
	v_pk_fma_f32 v[164:165], v[10:11], v[150:151], 0 op_sel_hi:[1,0,0]
	v_rcp_f32_e32 v160, v160
	v_pk_add_f32 v[162:163], v[162:163], 1.0 op_sel_hi:[1,0]
	v_rcp_f32_e32 v161, v161
	v_rcp_f32_e32 v162, v162
	v_rcp_f32_e32 v163, v163
	v_pk_fma_f32 v[150:151], v[12:13], v[150:151], 0 op_sel_hi:[1,0,0]
	v_add_u32_e32 v149, 0xa0, v140
	v_pk_mul_f32 v[158:159], v[158:159], v[160:161]
	v_pk_mul_f32 v[156:157], v[156:157], v[162:163]
	v_pk_mul_f32 v[158:159], v[164:165], v[158:159]
	v_pk_mul_f32 v[156:157], v[150:151], v[156:157]
	v_mad_i64_i32 v[150:151], s[38:39], v149, s36, v[142:143]
	v_lshl_add_u64 v[160:161], v[150:151], 0, v[144:145]
	v_cvt_pk_bf16_f32 v150, v154, v155
	v_cvt_pk_bf16_f32 v151, v152, v153
	v_cvt_pk_bf16_f32 v152, v158, v159
	v_cvt_pk_bf16_f32 v153, v156, v157
	v_add_u32_e32 v140, 0xb0, v140
	global_store_dwordx4 v[160:161], v[150:153], off sc1
	s_nop 1
	v_rsq_f32_e32 v150, v141
	s_nop 0
	v_pk_fma_f32 v[154:155], v[38:39], v[150:151], 0 op_sel_hi:[1,0,0]
	s_nop 0
	v_mul_f32_e32 v141, 0xbfb8aa3b, v154
	v_pk_fma_f32 v[152:153], v[40:41], v[150:151], 0 op_sel_hi:[1,0,0]
	v_exp_f32_e32 v156, v141
	v_mul_f32_e32 v141, 0xbfb8aa3b, v155
	v_exp_f32_e32 v157, v141
	v_mul_f32_e32 v141, 0xbfb8aa3b, v152
	v_exp_f32_e32 v158, v141
	v_mul_f32_e32 v141, 0xbfb8aa3b, v153
	v_exp_f32_e32 v159, v141
	v_pk_add_f32 v[156:157], v[156:157], 1.0 op_sel_hi:[1,0]
	v_pk_fma_f32 v[160:161], v[6:7], v[150:151], 0 op_sel_hi:[1,0,0]
	v_rcp_f32_e32 v156, v156
	v_pk_add_f32 v[158:159], v[158:159], 1.0 op_sel_hi:[1,0]
	v_rcp_f32_e32 v157, v157
	v_rcp_f32_e32 v158, v158
	v_rcp_f32_e32 v159, v159
	v_pk_fma_f32 v[162:163], v[8:9], v[150:151], 0 op_sel_hi:[1,0,0]
	v_pk_mul_f32 v[154:155], v[154:155], v[156:157]
	v_pk_fma_f32 v[156:157], v[36:37], v[150:151], 0 op_sel_hi:[1,0,0]
	v_pk_mul_f32 v[152:153], v[152:153], v[158:159]
	v_pk_fma_f32 v[158:159], v[34:35], v[150:151], 0 op_sel_hi:[1,0,0]
	v_pk_mul_f32 v[154:155], v[160:161], v[154:155]
	v_mul_f32_e32 v141, 0xbfb8aa3b, v158
	v_exp_f32_e32 v160, v141
	v_mul_f32_e32 v141, 0xbfb8aa3b, v159
	v_exp_f32_e32 v161, v141
	v_mul_f32_e32 v141, 0xbfb8aa3b, v156
	v_pk_mul_f32 v[152:153], v[162:163], v[152:153]
	v_exp_f32_e32 v162, v141
	v_mul_f32_e32 v141, 0xbfb8aa3b, v157
	v_exp_f32_e32 v163, v141
	v_pk_add_f32 v[160:161], v[160:161], 1.0 op_sel_hi:[1,0]
	v_mad_i64_i32 v[140:141], s[38:39], v140, s36, v[142:143]
	v_pk_add_f32 v[162:163], v[162:163], 1.0 op_sel_hi:[1,0]
	v_rcp_f32_e32 v160, v160
	v_rcp_f32_e32 v161, v161
	v_rcp_f32_e32 v162, v162
	v_rcp_f32_e32 v163, v163
	s_lshl_b32 s38, s2, 4
	s_ashr_i32 s39, s38, 31
	s_lshl_b64 s[38:39], s[38:39], 2
	v_readlane_b32 s36, v255, 11
	v_pk_fma_f32 v[164:165], v[2:3], v[150:151], 0 op_sel_hi:[1,0,0]
	v_pk_fma_f32 v[150:151], v[4:5], v[150:151], 0 op_sel_hi:[1,0,0]
	v_pk_mul_f32 v[158:159], v[158:159], v[160:161]
	v_pk_mul_f32 v[156:157], v[156:157], v[162:163]
	v_readlane_b32 s37, v255, 12
	s_add_u32 s36, s36, s38
	v_pk_mul_f32 v[150:151], v[150:151], v[156:157]
	v_pk_mul_f32 v[156:157], v[164:165], v[158:159]
	v_lshl_add_u64 v[144:145], v[140:141], 0, v[144:145]
	v_cvt_pk_bf16_f32 v140, v154, v155
	v_cvt_pk_bf16_f32 v141, v152, v153
	v_cvt_pk_bf16_f32 v142, v156, v157
	v_cvt_pk_bf16_f32 v143, v150, v151
	s_addc_u32 s37, s37, s39
	global_store_dwordx4 v[144:145], v[140:143], off sc1
	s_nop 1
	s_and_b64 s[38:39], s[26:27], exec
	s_cselect_b32 s39, 0, s37
	s_cselect_b32 s38, 0, s36
	s_and_b64 vcc, exec, s[50:51]
	s_cbranch_vccnz .LBB0_791
	v_mov_b64_e32 v[206:207], s[38:39]
	s_cbranch_execz .LBB0_792
